# v60 + attention step loops: back edge rotated so the loop-closing barrier is the loop head (counter test, slot rotation and branch run before the barrier)
# speedup vs baseline: 1.0106x; 1.0007x over previous
.LBB0_381:
	v_lshrrev_b32_e32 v0, 2, v81
	v_exp_f32_e32 v3, v84
	v_exp_f32_e32 v7, v83
	v_exp_f32_e32 v6, v49
	v_exp_f32_e32 v11, v48
	v_exp_f32_e32 v10, v51
	v_exp_f32_e32 v96, v50
	v_exp_f32_e32 v15, v53
	v_exp_f32_e32 v97, v52
	v_exp_f32_e32 v2, v55
	v_exp_f32_e32 v5, v54
	v_exp_f32_e32 v4, v57
	v_exp_f32_e32 v9, v56
	v_exp_f32_e32 v8, v59
	v_exp_f32_e32 v12, v58
	v_exp_f32_e32 v13, v61
	v_exp_f32_e32 v14, v60
	s_min_i32 s2, s29, 26
	v_and_or_b32 v0, v0, 3, v158
	v_lshlrev_b32_e32 v62, 1, v81
	s_sub_i32 s54, s2, s5
	v_lshlrev_b32_e32 v0, 6, v0
	v_and_b32_e32 v48, 32, v62
	v_mov_b32_e32 v155, v154
	s_mov_b32 s29, 1
	s_cmp_lt_i32 s54, -5
	v_or3_b32 v0, v48, v0, v82
	s_cbranch_scc1 .LBB0_391
	v_lshl_or_b32 v48, s5, 6, v158
	v_sub_u32_e32 v48, v48, v80
	v_subrev_u32_e32 v48, s53, v48
	s_lshl_b32 s2, s30, 8
	v_subrev_u32_e32 v162, s2, v48
	v_mov_b64_e32 v[62:63], v[46:47]
	s_add_i32 s54, s54, 8
	s_mov_b32 s30, 0x8000
	s_movk_i32 s53, 0x4000
	s_mov_b32 s2, 0
	s_mov_b32 s29, 3
	v_mov_b64_e32 v[60:61], v[44:45]
	v_mov_b64_e32 v[58:59], v[42:43]
	v_mov_b64_e32 v[56:57], v[40:41]
	v_mov_b64_e32 v[54:55], v[38:39]
	v_mov_b64_e32 v[52:53], v[36:37]
	v_mov_b64_e32 v[50:51], v[34:35]
	v_mov_b64_e32 v[48:49], v[32:33]
	s_branch .LBB0_383
.Lmy_h383:
	s_barrier

.LBB0_389:
	v_exp_f32_e32 v3, v164
	v_exp_f32_e32 v7, v163
	v_exp_f32_e32 v6, v82
	v_exp_f32_e32 v11, v15
	v_exp_f32_e32 v10, v84
	v_exp_f32_e32 v96, v83
	v_exp_f32_e32 v15, v86
	v_exp_f32_e32 v97, v85
	v_exp_f32_e32 v2, v88
	v_exp_f32_e32 v5, v87
	v_exp_f32_e32 v4, v90
	v_exp_f32_e32 v9, v89
	v_exp_f32_e32 v8, v92
	v_exp_f32_e32 v12, v91
	v_exp_f32_e32 v13, v80
	v_exp_f32_e32 v14, v14
	s_waitcnt vmcnt(0)
	s_add_i32 s2, s29, 2
	s_add_i32 s3, s29, 1
	s_cmp_lt_i32 s3, s54
	v_add_u32_e32 v162, 0x80, v162
	s_cbranch_scc0 .Lmy_x383
	s_mov_b32 s29, s2
	s_mov_b32 s2, s30
	s_mov_b32 s30, s55
	s_branch .Lmy_h383
.Lmy_x383:
	s_barrier
	s_branch .LBB0_392

.LBB0_398:
	s_lshl_b64 s[6:7], s[6:7], 20
	s_and_b64 s[34:35], s[40:41], exec
	v_lshlrev_b32_e32 v0, 4, v2
	s_cselect_b32 s72, s93, 0
	v_lshl_or_b32 v126, v35, 10, v0
	s_cselect_b32 s27, s94, 0x4000
	s_cselect_b32 s29, s95, 0x8000
	s_add_i32 s30, s72, 0
	v_add_u32_e32 v0, s30, v126
	s_waitcnt vmcnt(0)
	s_waitcnt vmcnt(0) lgkmcnt(0)
	s_barrier
	ds_read_b128 v[38:41], v0
	ds_read_b128 v[42:45], v0 offset:512
	s_mov_b32 s53, s52
	s_mov_b32 s54, s52
	s_mov_b32 s55, s52
	s_mov_b32 s56, s52
	s_mov_b32 s57, s52
	s_mov_b32 s58, s52
	s_mov_b32 s59, s52
	s_mov_b32 s60, s52
	s_mov_b32 s61, s52
	s_mov_b32 s62, s52
	s_mov_b32 s63, s52
	s_mov_b32 s64, s52
	s_mov_b32 s65, s52
	s_mov_b32 s66, s52
	s_mov_b32 s67, s52
	v_mov_b64_e32 v[2:3], s[52:53]
	v_mov_b64_e32 v[4:5], s[54:55]
	v_mov_b64_e32 v[6:7], s[56:57]
	v_mov_b64_e32 v[8:9], s[58:59]
	v_mov_b64_e32 v[10:11], s[60:61]
	v_mov_b64_e32 v[12:13], s[62:63]
	v_mov_b64_e32 v[14:15], s[64:65]
	v_mov_b64_e32 v[16:17], s[66:67]
	v_lshlrev_b32_e32 v124, 2, v35
	v_ashrrev_i32_e32 v115, 31, v114
	s_waitcnt lgkmcnt(1)
	v_mfma_f32_32x32x16_bf16 v[18:33], v[38:41], v[110:113], v[2:17]
	v_mov_b32_e32 v128, 0
	s_mov_b32 s55, -1
	s_mov_b32 s56, 0xc0000
	s_waitcnt lgkmcnt(0)
	v_mfma_f32_32x32x16_bf16 v[2:17], v[42:45], v[110:113], v[2:17]
	ds_read_b128 v[38:41], v0 offset:2048
	ds_read_b128 v[42:45], v0 offset:2560
	s_waitcnt lgkmcnt(1)
	v_mfma_f32_32x32x16_bf16 v[18:33], v[38:41], v[106:109], v[18:33]
	s_waitcnt lgkmcnt(0)
	v_mfma_f32_32x32x16_bf16 v[2:17], v[42:45], v[106:109], v[2:17]
	ds_read_b128 v[38:41], v0 offset:4096
	ds_read_b128 v[42:45], v0 offset:4608
	s_waitcnt lgkmcnt(1)
	v_mfma_f32_32x32x16_bf16 v[18:33], v[38:41], v[102:105], v[18:33]
	s_waitcnt lgkmcnt(0)
	v_mfma_f32_32x32x16_bf16 v[2:17], v[42:45], v[102:105], v[2:17]
	ds_read_b128 v[38:41], v0 offset:6656
	ds_read_b128 v[42:45], v0 offset:6144
	v_lshrrev_b32_e32 v0, 2, v34
	v_and_or_b32 v0, v0, 3, v124
	v_lshlrev_b32_e32 v34, 1, v34
	v_lshlrev_b32_e32 v0, 6, v0
	v_and_b32_e32 v34, 32, v34
	v_or3_b32 v125, v34, v0, v36
	s_waitcnt lgkmcnt(1)
	v_mfma_f32_32x32x16_bf16 v[2:17], v[38:41], v[98:101], v[2:17]
	s_waitcnt lgkmcnt(0)
	v_mfma_f32_32x32x16_bf16 v[18:33], v[42:45], v[98:101], v[18:33]
	s_nop 9
	v_max_f32_e32 v0, v3, v3
	s_nop 0
	v_max_f32_e32 v34, v19, v19
	v_max_f32_e32 v0, v34, v0
	v_max3_f32 v34, v18, v2, v20
	v_max3_f32 v0, v0, v21, v5
	v_max3_f32 v34, v34, v4, v22
	v_max3_f32 v0, v0, v23, v7
	v_max3_f32 v34, v34, v6, v24
	v_max3_f32 v0, v0, v25, v9
	v_max3_f32 v34, v34, v8, v26
	v_max3_f32 v0, v0, v27, v11
	v_max3_f32 v34, v34, v10, v28
	v_max3_f32 v0, v0, v29, v13
	v_max3_f32 v34, v34, v12, v30
	v_max3_f32 v0, v0, v31, v15
	v_max3_f32 v34, v34, v14, v32
	v_max3_f32 v0, v0, v33, v17
	v_max3_f32 v0, v34, v16, v0
	v_mov_b32_e32 v34, v0
	s_nop 1
	v_permlane32_swap_b32 v0, v34
	s_nop 1
	s_nop 0
	v_max_f32_e32 v34, v34, v34
	v_max_f32_e32 v0, v0, v0
	v_max_f32_e32 v0, v0, v34
	v_sub_f32_e32 v18, v18, v0
	v_sub_f32_e32 v19, v19, v0
	v_sub_f32_e32 v20, v20, v0
	v_sub_f32_e32 v21, v21, v0
	v_sub_f32_e32 v22, v22, v0
	v_sub_f32_e32 v23, v23, v0
	v_sub_f32_e32 v24, v24, v0
	v_sub_f32_e32 v25, v25, v0
	v_sub_f32_e32 v26, v26, v0
	v_sub_f32_e32 v27, v27, v0
	v_sub_f32_e32 v28, v28, v0
	v_sub_f32_e32 v29, v29, v0
	v_sub_f32_e32 v30, v30, v0
	v_sub_f32_e32 v31, v31, v0
	v_sub_f32_e32 v32, v32, v0
	v_sub_f32_e32 v33, v33, v0
	v_sub_f32_e32 v79, v15, v0
	v_sub_f32_e32 v78, v14, v0
	v_exp_f32_e32 v129, v18
	v_exp_f32_e32 v131, v19
	v_exp_f32_e32 v132, v20
	v_exp_f32_e32 v135, v21
	v_exp_f32_e32 v136, v22
	v_exp_f32_e32 v139, v23
	v_exp_f32_e32 v140, v24
	v_exp_f32_e32 v143, v25
	v_exp_f32_e32 v130, v26
	v_exp_f32_e32 v133, v27
	v_exp_f32_e32 v134, v28
	v_exp_f32_e32 v137, v29
	v_exp_f32_e32 v138, v30
	v_exp_f32_e32 v141, v31
	v_exp_f32_e32 v142, v32
	v_exp_f32_e32 v144, v33
	v_mov_b32_e32 v14, v1
	v_mov_b32_e32 v15, v1
	v_add_f32_e32 v127, 0, v0
	v_sub_f32_e32 v81, v17, v0
	v_sub_f32_e32 v80, v16, v0
	v_sub_f32_e32 v77, v13, v0
	v_sub_f32_e32 v76, v12, v0
	v_sub_f32_e32 v75, v11, v0
	v_sub_f32_e32 v74, v10, v0
	v_sub_f32_e32 v73, v9, v0
	v_sub_f32_e32 v72, v8, v0
	v_sub_f32_e32 v71, v7, v0
	v_sub_f32_e32 v70, v6, v0
	v_sub_f32_e32 v69, v5, v0
	v_sub_f32_e32 v68, v4, v0
	v_sub_f32_e32 v67, v3, v0
	v_sub_f32_e32 v66, v2, v0
	v_mov_b32_e32 v0, v1
	v_mov_b32_e32 v2, v1
	v_mov_b32_e32 v3, v1
	v_mov_b32_e32 v4, v1
	v_mov_b32_e32 v5, v1
	v_mov_b32_e32 v6, v1
	v_mov_b32_e32 v7, v1
	v_mov_b32_e32 v8, v1
	v_mov_b32_e32 v9, v1
	v_mov_b32_e32 v10, v1
	v_mov_b32_e32 v11, v1
	v_mov_b32_e32 v12, v1
	v_mov_b32_e32 v13, v1
	v_mov_b64_e32 v[32:33], v[14:15]
	v_xor_b32_e32 v50, 0x80000000, v127
	v_mov_b64_e32 v[30:31], v[12:13]
	v_mov_b64_e32 v[28:29], v[10:11]
	v_mov_b64_e32 v[26:27], v[8:9]
	v_mov_b64_e32 v[24:25], v[6:7]
	v_mov_b64_e32 v[22:23], v[4:5]
	v_mov_b64_e32 v[20:21], v[2:3]
	v_mov_b64_e32 v[18:19], v[0:1]
	v_mov_b64_e32 v[16:17], v[14:15]
	v_mov_b64_e32 v[14:15], v[12:13]
	v_mov_b64_e32 v[12:13], v[10:11]
	v_mov_b64_e32 v[10:11], v[8:9]
	v_mov_b64_e32 v[8:9], v[6:7]
	v_mov_b64_e32 v[6:7], v[4:5]
	v_mov_b64_e32 v[4:5], v[2:3]
	v_mov_b64_e32 v[2:3], v[0:1]
	v_mov_b32_e32 v51, v50
	v_mov_b32_e32 v52, v50
	v_mov_b32_e32 v53, v50
	v_mov_b32_e32 v54, v50
	v_mov_b32_e32 v55, v50
	v_mov_b32_e32 v56, v50
	v_mov_b32_e32 v57, v50
	v_mov_b32_e32 v58, v50
	v_mov_b32_e32 v59, v50
	v_mov_b32_e32 v60, v50
	v_mov_b32_e32 v61, v50
	v_mov_b32_e32 v62, v50
	v_mov_b32_e32 v63, v50
	v_mov_b32_e32 v64, v50
	v_mov_b32_e32 v65, v50
	s_branch .LBB0_399

.LBB0_404:
	v_exp_f32_e32 v129, v82
	s_setprio 0
	v_exp_f32_e32 v131, v83
	v_exp_f32_e32 v132, v84
	v_exp_f32_e32 v135, v85
	v_exp_f32_e32 v136, v86
	v_exp_f32_e32 v139, v87
	v_exp_f32_e32 v140, v88
	v_exp_f32_e32 v143, v89
	v_exp_f32_e32 v130, v90
	v_exp_f32_e32 v133, v91
	v_exp_f32_e32 v134, v92
	v_exp_f32_e32 v137, v93
	v_exp_f32_e32 v138, v94
	v_exp_f32_e32 v141, v95
	v_exp_f32_e32 v142, v96
	v_exp_f32_e32 v144, v97
	s_waitcnt vmcnt(0)
	s_add_i32 s55, s55, 2
	s_add_i32 s56, s56, 0x80000
	s_cmp_lt_u32 s55, 29
	s_cbranch_scc0 .Lmy_x399
	s_mov_b32 s72, s29
	s_mov_b32 s29, s30
	s_branch .Lmy_h399

.LBB0_421:
	s_lshl_b64 s[6:7], s[6:7], 20
	s_and_b64 s[28:29], s[40:41], exec
	v_lshlrev_b32_e32 v0, 4, v2
	s_cselect_b32 s40, s93, 0
	v_lshl_or_b32 v134, v35, 10, v0
	s_cselect_b32 s28, s94, 0x5000
	s_cselect_b32 s29, s95, 0xa000
	s_add_i32 s34, s40, 0
	v_add_u32_e32 v0, s34, v134
	s_waitcnt vmcnt(0)
	s_waitcnt vmcnt(0) lgkmcnt(0)
	s_barrier
	ds_read_b128 v[38:41], v0
	ds_read_b128 v[42:45], v0 offset:512
	s_mov_b32 s53, s52
	s_mov_b32 s54, s52
	s_mov_b32 s55, s52
	s_mov_b32 s56, s52
	s_mov_b32 s57, s52
	s_mov_b32 s58, s52
	s_mov_b32 s59, s52
	s_mov_b32 s60, s52
	s_mov_b32 s61, s52
	s_mov_b32 s62, s52
	s_mov_b32 s63, s52
	s_mov_b32 s64, s52
	s_mov_b32 s65, s52
	s_mov_b32 s66, s52
	s_mov_b32 s67, s52
	v_mov_b64_e32 v[2:3], s[52:53]
	v_mov_b64_e32 v[4:5], s[54:55]
	v_mov_b64_e32 v[6:7], s[56:57]
	v_mov_b64_e32 v[8:9], s[58:59]
	v_mov_b64_e32 v[10:11], s[60:61]
	v_mov_b64_e32 v[12:13], s[62:63]
	v_mov_b64_e32 v[14:15], s[64:65]
	v_mov_b64_e32 v[16:17], s[66:67]
	v_lshlrev_b32_e32 v132, 2, v35
	s_cmp_lt_i32 s30, 4
	s_waitcnt lgkmcnt(1)
	v_mfma_f32_32x32x16_bf16 v[18:33], v[38:41], v[118:121], v[2:17]
	s_cselect_b64 s[38:39], -1, 0
	s_cmp_gt_i32 s30, 3
	s_cselect_b64 s[34:35], -1, 0
	v_mov_b32_e32 v136, 0
	s_mov_b32 s57, -1
	s_mov_b32 s58, 0xc0000
	s_waitcnt lgkmcnt(0)
	v_mfma_f32_32x32x16_bf16 v[2:17], v[42:45], v[118:121], v[2:17]
	ds_read_b128 v[38:41], v0 offset:2048
	ds_read_b128 v[42:45], v0 offset:2560
	s_waitcnt lgkmcnt(1)
	v_mfma_f32_32x32x16_bf16 v[18:33], v[38:41], v[114:117], v[18:33]
	s_waitcnt lgkmcnt(0)
	v_mfma_f32_32x32x16_bf16 v[2:17], v[42:45], v[114:117], v[2:17]
	ds_read_b128 v[38:41], v0 offset:4096
	ds_read_b128 v[42:45], v0 offset:4608
	s_waitcnt lgkmcnt(1)
	v_mfma_f32_32x32x16_bf16 v[18:33], v[38:41], v[110:113], v[18:33]
	s_waitcnt lgkmcnt(0)
	v_mfma_f32_32x32x16_bf16 v[2:17], v[42:45], v[110:113], v[2:17]
	ds_read_b128 v[38:41], v0 offset:6144
	ds_read_b128 v[42:45], v0 offset:6656
	s_waitcnt lgkmcnt(1)
	v_mfma_f32_32x32x16_bf16 v[18:33], v[38:41], v[106:109], v[18:33]
	s_waitcnt lgkmcnt(0)
	v_mfma_f32_32x32x16_bf16 v[2:17], v[42:45], v[106:109], v[2:17]
	ds_read_b128 v[38:41], v0 offset:8192
	ds_read_b128 v[42:45], v0 offset:8704
	s_waitcnt lgkmcnt(1)
	v_mfma_f32_32x32x16_bf16 v[18:33], v[38:41], v[102:105], v[18:33]
	s_waitcnt lgkmcnt(0)
	v_mfma_f32_32x32x16_bf16 v[2:17], v[42:45], v[102:105], v[2:17]
	ds_read_b128 v[38:41], v0 offset:10752
	ds_read_b128 v[42:45], v0 offset:10240
	v_lshrrev_b32_e32 v0, 2, v34
	v_and_or_b32 v0, v0, 3, v132
	v_lshlrev_b32_e32 v34, 1, v34
	v_lshlrev_b32_e32 v0, 6, v0
	v_and_b32_e32 v34, 32, v34
	v_or3_b32 v133, v34, v0, v36
	s_waitcnt lgkmcnt(1)
	v_mfma_f32_32x32x16_bf16 v[2:17], v[38:41], v[98:101], v[2:17]
	s_waitcnt lgkmcnt(0)
	v_mfma_f32_32x32x16_bf16 v[18:33], v[42:45], v[98:101], v[18:33]
	s_nop 9
	v_max_f32_e32 v0, v3, v3
	s_nop 0
	v_max_f32_e32 v34, v19, v19
	v_max_f32_e32 v0, v34, v0
	v_max3_f32 v34, v18, v2, v20
	v_max3_f32 v0, v0, v21, v5
	v_max3_f32 v34, v34, v4, v22
	v_max3_f32 v0, v0, v23, v7
	v_max3_f32 v34, v34, v6, v24
	v_max3_f32 v0, v0, v25, v9
	v_max3_f32 v34, v34, v8, v26
	v_max3_f32 v0, v0, v27, v11
	v_max3_f32 v34, v34, v10, v28
	v_max3_f32 v0, v0, v29, v13
	v_max3_f32 v34, v34, v12, v30
	v_max3_f32 v0, v0, v31, v15
	v_max3_f32 v34, v34, v14, v32
	v_max3_f32 v0, v0, v33, v17
	v_max3_f32 v0, v34, v16, v0
	v_mov_b32_e32 v34, v0
	s_nop 1
	v_permlane32_swap_b32 v0, v34
	s_nop 1
	s_nop 0
	v_max_f32_e32 v34, v34, v34
	v_max_f32_e32 v0, v0, v0
	v_max_f32_e32 v0, v0, v34
	v_sub_f32_e32 v18, v18, v0
	v_sub_f32_e32 v19, v19, v0
	v_sub_f32_e32 v20, v20, v0
	v_sub_f32_e32 v21, v21, v0
	v_sub_f32_e32 v22, v22, v0
	v_sub_f32_e32 v23, v23, v0
	v_sub_f32_e32 v24, v24, v0
	v_sub_f32_e32 v25, v25, v0
	v_sub_f32_e32 v26, v26, v0
	v_sub_f32_e32 v27, v27, v0
	v_sub_f32_e32 v28, v28, v0
	v_sub_f32_e32 v29, v29, v0
	v_sub_f32_e32 v30, v30, v0
	v_sub_f32_e32 v31, v31, v0
	v_sub_f32_e32 v32, v32, v0
	v_sub_f32_e32 v33, v33, v0
	v_sub_f32_e32 v79, v15, v0
	v_sub_f32_e32 v78, v14, v0
	v_exp_f32_e32 v141, v18
	v_exp_f32_e32 v146, v19
	v_exp_f32_e32 v138, v20
	v_exp_f32_e32 v142, v21
	v_exp_f32_e32 v143, v22
	v_exp_f32_e32 v147, v23
	v_exp_f32_e32 v148, v24
	v_exp_f32_e32 v151, v25
	v_exp_f32_e32 v137, v26
	v_exp_f32_e32 v139, v27
	v_exp_f32_e32 v140, v28
	v_exp_f32_e32 v144, v29
	v_exp_f32_e32 v145, v30
	v_exp_f32_e32 v149, v31
	v_exp_f32_e32 v150, v32
	v_exp_f32_e32 v152, v33
	v_mov_b32_e32 v14, v1
	v_mov_b32_e32 v15, v1
	v_add_f32_e32 v135, 0, v0
	v_sub_f32_e32 v81, v17, v0
	v_sub_f32_e32 v80, v16, v0
	v_sub_f32_e32 v77, v13, v0
	v_sub_f32_e32 v76, v12, v0
	v_sub_f32_e32 v75, v11, v0
	v_sub_f32_e32 v74, v10, v0
	v_sub_f32_e32 v73, v9, v0
	v_sub_f32_e32 v72, v8, v0
	v_sub_f32_e32 v71, v7, v0
	v_sub_f32_e32 v70, v6, v0
	v_sub_f32_e32 v69, v5, v0
	v_sub_f32_e32 v68, v4, v0
	v_sub_f32_e32 v67, v3, v0
	v_sub_f32_e32 v66, v2, v0
	v_mov_b32_e32 v0, v1
	v_mov_b32_e32 v2, v1
	v_mov_b32_e32 v3, v1
	v_mov_b32_e32 v4, v1
	v_mov_b32_e32 v5, v1
	v_mov_b32_e32 v6, v1
	v_mov_b32_e32 v7, v1
	v_mov_b32_e32 v8, v1
	v_mov_b32_e32 v9, v1
	v_mov_b32_e32 v10, v1
	v_mov_b32_e32 v11, v1
	v_mov_b32_e32 v12, v1
	v_mov_b32_e32 v13, v1
	v_mov_b64_e32 v[32:33], v[14:15]
	v_xor_b32_e32 v50, 0x80000000, v135
	v_mov_b64_e32 v[30:31], v[12:13]
	v_mov_b64_e32 v[28:29], v[10:11]
	v_mov_b64_e32 v[26:27], v[8:9]
	v_mov_b64_e32 v[24:25], v[6:7]
	v_mov_b64_e32 v[22:23], v[4:5]
	v_mov_b64_e32 v[20:21], v[2:3]
	v_mov_b64_e32 v[18:19], v[0:1]
	v_mov_b64_e32 v[16:17], v[14:15]
	v_mov_b64_e32 v[14:15], v[12:13]
	v_mov_b64_e32 v[12:13], v[10:11]
	v_mov_b64_e32 v[10:11], v[8:9]
	v_mov_b64_e32 v[8:9], v[6:7]
	v_mov_b64_e32 v[6:7], v[4:5]
	v_mov_b64_e32 v[4:5], v[2:3]
	v_mov_b64_e32 v[2:3], v[0:1]
	v_mov_b32_e32 v51, v50
	v_mov_b32_e32 v52, v50
	v_mov_b32_e32 v53, v50
	v_mov_b32_e32 v54, v50
	v_mov_b32_e32 v55, v50
	v_mov_b32_e32 v56, v50
	v_mov_b32_e32 v57, v50
	v_mov_b32_e32 v58, v50
	v_mov_b32_e32 v59, v50
	v_mov_b32_e32 v60, v50
	v_mov_b32_e32 v61, v50
	v_mov_b32_e32 v62, v50
	v_mov_b32_e32 v63, v50
	v_mov_b32_e32 v64, v50
	v_mov_b32_e32 v65, v50
	s_branch .LBB0_422

.LBB0_431:
	v_exp_f32_e32 v141, v82
	s_setprio 0
	v_exp_f32_e32 v146, v83
	v_exp_f32_e32 v138, v84
	v_exp_f32_e32 v142, v85
	v_exp_f32_e32 v143, v86
	v_exp_f32_e32 v147, v87
	v_exp_f32_e32 v148, v88
	v_exp_f32_e32 v151, v89
	v_exp_f32_e32 v137, v90
	v_exp_f32_e32 v139, v91
	v_exp_f32_e32 v140, v92
	v_exp_f32_e32 v144, v93
	v_exp_f32_e32 v145, v94
	v_exp_f32_e32 v149, v95
	v_exp_f32_e32 v150, v96
	v_exp_f32_e32 v152, v97
	s_mov_b32 s78, s76
	s_waitcnt vmcnt(0)
	s_add_i32 s57, s57, 2
	s_add_i32 s58, s58, 0x80000
	s_cmp_lt_u32 s57, 29
	s_cbranch_scc0 .Lmy_x422
	s_mov_b32 s40, s29
	s_mov_b32 s29, s30
	s_branch .Lmy_h422
